# P1/P5 accumulator zeroing with 64-bit moves (64 instead of 127 VALU per tile)
# speedup vs baseline: 1.0150x; 1.0150x over previous
; template <class Epi, class Sched, bool ALIGN_EPI = false, bool SP2 = false, bool SPLITK = false>
; __device__ __forceinline__ void gemm_phase(PG8_LAS unsigned char* lds, const Gemm g, const Sched& S, const Epi& E) {
;     ...
; #pragma unroll
;         for (int a = 0; a < 2; ++a)
; #pragma unroll
;             for (int b = 0; b < 2; ++b)
; #pragma unroll
;                 for (int m = 0; m < 4; ++m)
; #pragma unroll
;                     for (int n = 0; n < 2; ++n) acc[a][b][m][n] = (f32x4){0.f, 0.f, 0.f, 0.f};
;         cur = nxt; cA = nA; cB = nB; ++ui;
.LBB0_164:
	s_ashr_i32 s35, s34, 31
	s_lshl_b64 s[22:23], s[34:35], 19
	s_add_u32 s36, s82, s22
	s_addc_u32 s37, s83, s23
	s_and_b64 s[22:23], s[38:39], exec
	s_cselect_b32 s4, s37, s49
	s_cselect_b32 s12, s36, s48
	s_ashr_i32 s21, s20, 31
	s_lshl_b64 s[22:23], s[20:21], 19
	v_readlane_b32 s21, v255, 45
	s_add_u32 s40, s21, s22
	v_readlane_b32 s21, v255, 46
	s_addc_u32 s41, s21, s23
	s_and_b64 s[22:23], s[38:39], exec
	s_cselect_b32 s21, s41, s47
	s_cselect_b32 s22, s40, s46
	s_add_u32 s54, s48, 0x40080
	s_addc_u32 s55, s49, 0
	s_add_u32 s23, s46, 0x100
	v_mov_b32_e32 v2, 0
	s_addc_u32 s24, s47, 0
	s_mov_b32 s25, -2
	v_mov_b32_e32 v3, 0
	v_mov_b64_e32 v[4:5], 0
	v_mov_b64_e32 v[6:7], 0
	v_mov_b64_e32 v[8:9], 0
	v_mov_b64_e32 v[10:11], 0
	v_mov_b64_e32 v[12:13], 0
	v_mov_b64_e32 v[14:15], 0
	v_mov_b64_e32 v[16:17], 0
	v_mov_b64_e32 v[18:19], 0
	v_mov_b64_e32 v[20:21], 0
	v_mov_b64_e32 v[22:23], 0
	v_mov_b64_e32 v[24:25], 0
	v_mov_b64_e32 v[26:27], 0
	v_mov_b64_e32 v[28:29], 0
	v_mov_b64_e32 v[30:31], 0
	v_mov_b64_e32 v[32:33], 0
	v_mov_b64_e32 v[34:35], 0
	v_mov_b64_e32 v[36:37], 0
	v_mov_b64_e32 v[38:39], 0
	v_mov_b64_e32 v[40:41], 0
	v_mov_b64_e32 v[42:43], 0
	v_mov_b64_e32 v[44:45], 0
	v_mov_b64_e32 v[46:47], 0
	v_mov_b64_e32 v[48:49], 0
	v_mov_b64_e32 v[50:51], 0
	v_mov_b64_e32 v[52:53], 0
	v_mov_b64_e32 v[54:55], 0
	v_mov_b64_e32 v[56:57], 0
	v_mov_b64_e32 v[58:59], 0
	v_mov_b64_e32 v[60:61], 0
	v_mov_b64_e32 v[62:63], 0
	v_mov_b64_e32 v[64:65], 0
	v_mov_b64_e32 v[66:67], 0
	v_mov_b64_e32 v[68:69], 0
	v_mov_b64_e32 v[70:71], 0
	v_mov_b64_e32 v[72:73], 0
	v_mov_b64_e32 v[74:75], 0
	v_mov_b64_e32 v[76:77], 0
	v_mov_b64_e32 v[78:79], 0
	v_mov_b64_e32 v[80:81], 0
	v_mov_b64_e32 v[82:83], 0
	v_mov_b64_e32 v[84:85], 0
	v_mov_b64_e32 v[86:87], 0
	v_mov_b64_e32 v[88:89], 0
	v_mov_b64_e32 v[90:91], 0
	v_mov_b64_e32 v[92:93], 0
	v_mov_b64_e32 v[94:95], 0
	v_mov_b64_e32 v[96:97], 0
	v_mov_b64_e32 v[98:99], 0
	v_mov_b64_e32 v[100:101], 0
	v_mov_b64_e32 v[102:103], 0
	v_mov_b64_e32 v[104:105], 0
	v_mov_b64_e32 v[106:107], 0
	v_mov_b64_e32 v[108:109], 0
	v_mov_b64_e32 v[110:111], 0
	v_mov_b64_e32 v[112:113], 0
	v_mov_b64_e32 v[114:115], 0
	v_mov_b64_e32 v[116:117], 0
	v_mov_b64_e32 v[118:119], 0
	v_mov_b64_e32 v[120:121], 0
	v_mov_b64_e32 v[122:123], 0
	v_mov_b64_e32 v[124:125], 0
	v_mov_b64_e32 v[126:127], 0
	v_mov_b64_e32 v[128:129], 0

; template <class Epi, class Sched, bool ALIGN_EPI = false, bool SP2 = false, bool SPLITK = false>
; __device__ __forceinline__ void gemm_phase(PG8_LAS unsigned char* lds, const Gemm g, const Sched& S, const Epi& E) {
;     ...
; #pragma unroll
;         for (int a = 0; a < 2; ++a)
; #pragma unroll
;             for (int b = 0; b < 2; ++b)
; #pragma unroll
;                 for (int m = 0; m < 4; ++m)
; #pragma unroll
;                     for (int n = 0; n < 2; ++n) acc[a][b][m][n] = (f32x4){0.f, 0.f, 0.f, 0.f};
;         cur = nxt; cA = nA; cB = nB; ++ui;
.LBB0_581:
	s_ashr_i32 s21, s20, 31
	s_lshl_b64 s[34:35], s[20:21], 19
	s_add_u32 s34, s82, s34
	s_addc_u32 s35, s83, s35
	s_and_b64 s[36:37], s[38:39], exec
	s_cselect_b32 s4, s35, s43
	s_cselect_b32 s12, s34, s42
	s_ashr_i32 s19, s18, 31
	s_lshl_b64 s[36:37], s[18:19], 19
	s_add_u32 s36, s33, s36
	s_addc_u32 s37, s50, s37
	s_and_b64 s[48:49], s[38:39], exec
	s_cselect_b32 s19, s37, s47
	s_cselect_b32 s21, s36, s46
	s_add_u32 s42, s42, 0x40080
	s_addc_u32 s43, s43, 0
	s_add_u32 s25, s46, 0x100
	v_mov_b32_e32 v2, 0
	s_addc_u32 s41, s47, 0
	s_mov_b32 s45, -2
	v_mov_b32_e32 v3, 0
	v_mov_b64_e32 v[4:5], 0
	v_mov_b64_e32 v[6:7], 0
	v_mov_b64_e32 v[8:9], 0
	v_mov_b64_e32 v[10:11], 0
	v_mov_b64_e32 v[12:13], 0
	v_mov_b64_e32 v[14:15], 0
	v_mov_b64_e32 v[16:17], 0
	v_mov_b64_e32 v[18:19], 0
	v_mov_b64_e32 v[20:21], 0
	v_mov_b64_e32 v[22:23], 0
	v_mov_b64_e32 v[24:25], 0
	v_mov_b64_e32 v[26:27], 0
	v_mov_b64_e32 v[28:29], 0
	v_mov_b64_e32 v[30:31], 0
	v_mov_b64_e32 v[32:33], 0
	v_mov_b64_e32 v[34:35], 0
	v_mov_b64_e32 v[36:37], 0
	v_mov_b64_e32 v[38:39], 0
	v_mov_b64_e32 v[40:41], 0
	v_mov_b64_e32 v[42:43], 0
	v_mov_b64_e32 v[44:45], 0
	v_mov_b64_e32 v[46:47], 0
	v_mov_b64_e32 v[48:49], 0
	v_mov_b64_e32 v[50:51], 0
	v_mov_b64_e32 v[52:53], 0
	v_mov_b64_e32 v[54:55], 0
	v_mov_b64_e32 v[56:57], 0
	v_mov_b64_e32 v[58:59], 0
	v_mov_b64_e32 v[60:61], 0
	v_mov_b64_e32 v[62:63], 0
	v_mov_b64_e32 v[64:65], 0
	v_mov_b64_e32 v[66:67], 0
	v_mov_b64_e32 v[68:69], 0
	v_mov_b64_e32 v[70:71], 0
	v_mov_b64_e32 v[72:73], 0
	v_mov_b64_e32 v[74:75], 0
	v_mov_b64_e32 v[76:77], 0
	v_mov_b64_e32 v[78:79], 0
	v_mov_b64_e32 v[80:81], 0
	v_mov_b64_e32 v[82:83], 0
	v_mov_b64_e32 v[84:85], 0
	v_mov_b64_e32 v[86:87], 0
	v_mov_b64_e32 v[88:89], 0
	v_mov_b64_e32 v[90:91], 0
	v_mov_b64_e32 v[92:93], 0
	v_mov_b64_e32 v[94:95], 0
	v_mov_b64_e32 v[96:97], 0
	v_mov_b64_e32 v[98:99], 0
	v_mov_b64_e32 v[100:101], 0
	v_mov_b64_e32 v[102:103], 0
	v_mov_b64_e32 v[104:105], 0
	v_mov_b64_e32 v[106:107], 0
	v_mov_b64_e32 v[108:109], 0
	v_mov_b64_e32 v[110:111], 0
	v_mov_b64_e32 v[112:113], 0
	v_mov_b64_e32 v[114:115], 0
	v_mov_b64_e32 v[116:117], 0
	v_mov_b64_e32 v[118:119], 0
	v_mov_b64_e32 v[120:121], 0
	v_mov_b64_e32 v[122:123], 0
	v_mov_b64_e32 v[124:125], 0
	v_mov_b64_e32 v[126:127], 0
	v_mov_b64_e32 v[128:129], 0
